# phase B last half round K-split across CU pairs (f32 partial accumulators exchanged through dead M region), on top of QK-norm fusion
# speedup vs baseline: 1.0079x; 1.0027x over previous
; __global__ void __launch_bounds__(NTHREADS, 2) fwd_kernel(Params p) {
;     ...
;         int ph = phi, cb = cblk, Gv = G; asm volatile("" : "+s"(ph), "+s"(cb), "+s"(Gv));
;         {
;             const int q = ph - 1, chunk = q / STEPS, step = q % STEPS, layer = step >= 8 ? 1 : 0, sub = step == 0 ? 0 : (step - 1) % 7 + 1;
.LBB0_127:
	s_mov_b32 s98, 0
	s_mov_b32 s99, 0
	s_mov_b32 s0, s90
	s_mov_b32 s24, s23
	s_mov_b32 s1, s91
	s_nop 0
	v_writelane_b32 v255, s1, 0
	v_writelane_b32 v255, s0, 1
	s_add_i32 s0, s24, -1
	s_mul_hi_i32 s1, s0, 0x88888889
	s_add_i32 s1, s1, s0
	s_lshr_b32 s2, s1, 31
	s_ashr_i32 s1, s1, 3
	s_add_i32 s4, s1, s2
	s_mul_i32 s1, s4, 15
	s_sub_i32 s0, s0, s1
	s_mov_b32 s1, s71
	s_cmp_eq_u32 s0, 0
	v_writelane_b32 v255, s1, 2
	s_cbranch_scc1 .LBB0_129
	s_add_i32 s1, s0, -1
	s_bfe_i32 s2, s1, 0x80000
	s_mul_i32 s2, s2, 0xff93
	s_bfe_u32 s2, s2, 0x80008
	s_add_i32 s2, s2, s1
	s_bfe_i32 s3, s2, 0x80000
	s_sext_i32_i16 s3, s3
	s_ashr_i32 s3, s3, 2
	s_bfe_u32 s2, s2, 0x10007
	s_add_i32 s2, s3, s2
	s_mul_i32 s2, s2, 7
	s_sub_i32 s1, s1, s2
	s_add_i32 s1, s1, 1
	s_sext_i32_i8 s1, s1
	v_writelane_b32 v255, s1, 2

; template <class Epi, class Sched>
; __device__ __forceinline__ void gemm_phase(LAS unsigned char* lds_in, const int lda, const int ldb, const Sched& S, const Epi& E, const int WID) {
;     ...
; #pragma unroll
;         for (int a = 0; a < 2; ++a)
; #pragma unroll
;             for (int b = 0; b < 2; ++b)
; #pragma unroll
;                 for (int m = 0; m < 4; ++m)
; #pragma unroll
;                     for (int n = 0; n < 2; ++n) acc[a][b][m][n] = (f32x4){0.f, 0.f, 0.f, 0.f};
;         cur = nxt; cA = nA; cB = nB; ++ui;
;     __device__ __forceinline__ bool next(int i, Unit& u) const {
;         const int L = i * G + c; if (L >= 2688) return false; u.nt = 32;
;         if (L < 2304) { pg8::remap(L, 64, 36, u.pm, u.pn); u.pn += 12; if (u.pn >= 36) u.pn -= 36; u.aux = 0;
;              u.A = H + (size_t)u.pm * 256 * 2048 * 2; u.B = W + (size_t)(1536 + u.pn * 256) * 2048 * 2; }
;         else { pg8::remap(L - 2304, 6, 64, u.pm, u.pn); u.aux = 1; u.A = W + (size_t)u.pm * 256 * 2048 * 2; u.B = H + (size_t)u.pn * 256 * 2048 * 2; }
.LBB0_1033:
	s_mov_b32 s99, s98
	s_and_b64 vcc, exec, s[6:7]
	s_mov_b32 s94, s9
	s_mov_b32 s16, s8
	s_mov_b32 s0, s10
	s_mov_b64 s[20:21], s[14:15]
	s_mov_b64 s[18:19], s[12:13]
	s_cbranch_vccnz .LBB0_1144
.LBB0_1034:
	s_add_i32 s93, s93, 1
	v_readlane_b32 s1, v255, 0
	s_mul_i32 s1, s93, s1
	v_readlane_b32 s6, v255, 1
	s_add_i32 s1, s1, s6
	s_mov_b32 s98, 0
	s_cmpk_lt_i32 s1, 0xa00
	s_cbranch_scc1 .Lks_nosplit
	s_cmpk_gt_i32 s1, 0xaff
	s_cbranch_scc1 .Lks_nosplit
	s_sub_i32 s6, s1, 0xa00
	s_lshr_b32 s98, s6, 7
	s_add_i32 s98, s98, 1
	s_and_b32 s6, s6, 0x7f
	s_add_i32 s1, s6, 0xa00
.Lks_nosplit:
	s_cmpk_gt_i32 s1, 0xa7f
	s_cselect_b64 s[6:7], -1, 0
	s_and_b64 vcc, exec, s[6:7]
	s_cbranch_vccnz .LBB0_1039
	s_cmpk_gt_i32 s1, 0x8ff
	s_mov_b64 s[22:23], -1
	s_cbranch_scc0 .LBB0_1037
	s_and_b32 s8, s1, 7
	s_add_i32 s9, s1, 0xf700
	s_mul_i32 s8, s8, 48
	s_bfe_u32 s9, s9, 0xd0003
	s_add_i32 s9, s9, s8
	s_and_b32 s8, s9, 0xffff
	s_mul_i32 s8, s8, 0xaaab
	s_lshr_b32 s8, s8, 18
	s_mul_i32 s10, s8, 6
	s_sub_i32 s9, s9, s10
	s_and_b32 s70, s9, 0xffff
	s_lshl_b64 s[10:11], s[70:71], 20
	v_readlane_b32 s9, v255, 6
	s_add_u32 s12, s9, s10
	v_readlane_b32 s9, v255, 7
	s_addc_u32 s13, s9, s11
	s_mov_b32 s9, s71
	s_lshl_b64 s[10:11], s[8:9], 20
	s_add_u32 s14, s28, s10
	s_addc_u32 s15, s29, s11
	s_mov_b64 s[22:23], 0
	s_mov_b32 s10, s70
	s_cmp_eq_u32 s98, 2
	s_cbranch_scc0 .Lks_noff
	s_add_u32 s12, s12, 0x800
	s_addc_u32 s13, s13, 0
	s_add_u32 s14, s14, 0x800
	s_addc_u32 s15, s15, 0
.Lks_noff:
.LBB0_1037:
	s_andn2_b64 vcc, exec, s[22:23]
	s_mov_b32 s9, 1
	s_cbranch_vccnz .LBB0_1039
	s_ashr_i32 s8, s1, 31
	s_lshr_b32 s8, s8, 29
	s_add_i32 s8, s1, s8
	s_ashr_i32 s10, s8, 3
	s_and_b32 s8, s8, -8
	s_sub_i32 s1, s1, s8
	s_cmp_lt_i32 s1, 0
	s_cselect_b32 s8, s80, 0x120
	s_mul_i32 s1, s8, s1
	s_add_i32 s1, s1, s10
	s_mul_hi_i32 s8, s1, 0x38e38e39
	s_lshr_b32 s10, s8, 31
	s_ashr_i32 s8, s8, 6
	s_add_i32 s8, s8, s10
	s_lshl_b32 s10, s8, 3
	s_mulk_i32 s8, 0x120
	s_sub_i32 s1, s1, s8
	s_bfe_u32 s8, s1, 0x3001c
	s_add_i32 s8, s1, s8
	s_sext_i32_i16 s11, s8
	s_and_b32 s8, s8, 0xfff8
	s_sub_i32 s8, s1, s8
	s_sext_i32_i16 s8, s8
	s_add_i32 s10, s10, s8
	s_ashr_i32 s8, s11, 3
	s_cmpk_gt_i32 s1, 0xbf
	s_cselect_b32 s1, 0xffffffe8, 12
	s_ashr_i32 s11, s10, 31
	s_add_i32 s8, s1, s8
	s_lshl_b64 s[12:13], s[10:11], 20
	s_add_u32 s12, s28, s12
	s_addc_u32 s13, s29, s13
	s_lshl_b32 s14, s8, 8
	s_ashr_i32 s15, s14, 31
	s_lshl_b64 s[14:15], s[14:15], 12
	v_readlane_b32 s1, v255, 6
	s_add_u32 s1, s1, s14
	v_readlane_b32 s11, v255, 7
	s_addc_u32 s11, s11, s15
	s_add_u32 s14, s1, 0x600000
	s_mov_b32 s9, 0
	s_addc_u32 s15, s11, 0
.LBB0_1039:
	s_add_u32 s18, s18, 0x80080
	s_addc_u32 s19, s19, 0
	s_add_u32 s1, s20, 0x100
	v_mov_b32_e32 v2, 0
	s_addc_u32 s11, s21, 0
	s_mov_b32 s70, -2
	s_cmp_eq_u32 s99, 0
	s_cselect_b32 s32, 28, 12
	v_mov_b32_e32 v3, v2
	v_mov_b32_e32 v4, v2
	v_mov_b32_e32 v5, v2
	v_mov_b32_e32 v6, v2
	v_mov_b32_e32 v7, v2
	v_mov_b32_e32 v8, v2
	v_mov_b32_e32 v9, v2
	v_mov_b32_e32 v10, v2
	v_mov_b32_e32 v11, v2
	v_mov_b32_e32 v12, v2
	v_mov_b32_e32 v13, v2
	v_mov_b32_e32 v14, v2
	v_mov_b32_e32 v15, v2
	v_mov_b32_e32 v16, v2
	v_mov_b32_e32 v17, v2
	v_mov_b32_e32 v18, v2
	v_mov_b32_e32 v19, v2
	v_mov_b32_e32 v20, v2
	v_mov_b32_e32 v21, v2
	v_mov_b32_e32 v22, v2
	v_mov_b32_e32 v23, v2
	v_mov_b32_e32 v24, v2
	v_mov_b32_e32 v25, v2
	v_mov_b32_e32 v26, v2
	v_mov_b32_e32 v27, v2
	v_mov_b32_e32 v28, v2
	v_mov_b32_e32 v29, v2
	v_mov_b32_e32 v30, v2
	v_mov_b32_e32 v31, v2
	v_mov_b32_e32 v32, v2
	v_mov_b32_e32 v33, v2
	v_mov_b32_e32 v66, v2
	v_mov_b32_e32 v67, v2
	v_mov_b32_e32 v68, v2
	v_mov_b32_e32 v69, v2
	v_mov_b32_e32 v70, v2
	v_mov_b32_e32 v71, v2
	v_mov_b32_e32 v72, v2
	v_mov_b32_e32 v73, v2
	v_mov_b32_e32 v74, v2
	v_mov_b32_e32 v75, v2
	v_mov_b32_e32 v76, v2
	v_mov_b32_e32 v77, v2
	v_mov_b32_e32 v78, v2
	v_mov_b32_e32 v79, v2
	v_mov_b32_e32 v80, v2
	v_mov_b32_e32 v81, v2
	v_mov_b32_e32 v82, v2
	v_mov_b32_e32 v83, v2
	v_mov_b32_e32 v84, v2
	v_mov_b32_e32 v85, v2
	v_mov_b32_e32 v86, v2
	v_mov_b32_e32 v87, v2
	v_mov_b32_e32 v88, v2
	v_mov_b32_e32 v89, v2
	v_mov_b32_e32 v90, v2
	v_mov_b32_e32 v91, v2
	v_mov_b32_e32 v92, v2
	v_mov_b32_e32 v93, v2
	v_mov_b32_e32 v94, v2
	v_mov_b32_e32 v95, v2
	v_mov_b32_e32 v96, v2
	v_mov_b32_e32 v97, v2
	v_mov_b32_e32 v34, v2
	v_mov_b32_e32 v35, v2
	v_mov_b32_e32 v36, v2
	v_mov_b32_e32 v37, v2
	v_mov_b32_e32 v38, v2
	v_mov_b32_e32 v39, v2
	v_mov_b32_e32 v40, v2
	v_mov_b32_e32 v41, v2
	v_mov_b32_e32 v42, v2
	v_mov_b32_e32 v43, v2
	v_mov_b32_e32 v44, v2
	v_mov_b32_e32 v45, v2
	v_mov_b32_e32 v46, v2
	v_mov_b32_e32 v47, v2
	v_mov_b32_e32 v48, v2
	v_mov_b32_e32 v49, v2
	v_mov_b32_e32 v50, v2
	v_mov_b32_e32 v51, v2
	v_mov_b32_e32 v52, v2
	v_mov_b32_e32 v53, v2
	v_mov_b32_e32 v54, v2
	v_mov_b32_e32 v55, v2
	v_mov_b32_e32 v56, v2
	v_mov_b32_e32 v57, v2
	v_mov_b32_e32 v58, v2
	v_mov_b32_e32 v59, v2
	v_mov_b32_e32 v60, v2
	v_mov_b32_e32 v61, v2
	v_mov_b32_e32 v62, v2
	v_mov_b32_e32 v63, v2
	v_mov_b32_e32 v64, v2
	v_mov_b32_e32 v65, v2
	v_mov_b32_e32 v98, v2
	v_mov_b32_e32 v99, v2
	v_mov_b32_e32 v100, v2
	v_mov_b32_e32 v101, v2
	v_mov_b32_e32 v102, v2
	v_mov_b32_e32 v103, v2
	v_mov_b32_e32 v104, v2
	v_mov_b32_e32 v105, v2
	v_mov_b32_e32 v106, v2
	v_mov_b32_e32 v107, v2
	v_mov_b32_e32 v108, v2
	v_mov_b32_e32 v109, v2
	v_mov_b32_e32 v110, v2
	v_mov_b32_e32 v111, v2
	v_mov_b32_e32 v112, v2
	v_mov_b32_e32 v113, v2
	v_mov_b32_e32 v114, v2
	v_mov_b32_e32 v115, v2
	v_mov_b32_e32 v116, v2
	v_mov_b32_e32 v117, v2
	v_mov_b32_e32 v118, v2
	v_mov_b32_e32 v119, v2
	v_mov_b32_e32 v120, v2
	v_mov_b32_e32 v121, v2
	v_mov_b32_e32 v122, v2
	v_mov_b32_e32 v123, v2
	v_mov_b32_e32 v124, v2
	v_mov_b32_e32 v125, v2
	v_mov_b32_e32 v126, v2
	v_mov_b32_e32 v127, v2
	v_mov_b32_e32 v128, v2
	v_mov_b32_e32 v129, v2
; #define PG8_STAGE(bufoff, gbase, voff) do { _Pragma("unroll") for (int _i = 0; _i < 2; ++_i) \
;         __builtin_amdgcn_global_load_lds((const unsigned*)((const char*)(gbase) + (voff)[_i]), (LAS unsigned*)(lds + (bufoff) + ldsw + _i * 8192), 16, 0, 0); } while (0)
; #define PG8_LDA(dst, b, h) do { _Pragma("unroll") for (int m = 0; m < 4; ++m) _Pragma("unroll") for (int k = 0; k < 2; ++k) dst[m][k] = *(const LAS bf16x8*)(lds + PG8_SA(b, h) + aoff + m * 2048 + k * 1024); } while (0)
; #define PG8_LDB(dst, b, h) do { _Pragma("unroll") for (int n = 0; n < 2; ++n) _Pragma("unroll") for (int k = 0; k < 2; ++k) dst[n][k] = *(const LAS bf16x8*)(lds + PG8_SB(b, h) + boff + n * 2048 + k * 1024); } while (0)
; #define PG8_MMA(ai, bj, At, Bt) do { __builtin_amdgcn_s_setprio(1); _Pragma("unroll") for (int m = 0; m < 4; ++m) _Pragma("unroll") for (int n = 0; n < 2; ++n) _Pragma("unroll") for (int k = 0; k < 2; ++k) \
;         acc[ai][bj][m][n] = __builtin_amdgcn_mfma_f32_16x16x32_bf16(Bt[n][k], At[m][k], acc[ai][bj][m][n], 0, 0, 0); __builtin_amdgcn_s_setprio(0); } while (0)
; #define PG8_WAIT_L(n) asm volatile("s_waitcnt lgkmcnt(" #n ")" ::: "memory")
; #define PG8_BAR __builtin_amdgcn_s_barrier()
; #define PG8_SCHED __builtin_amdgcn_sched_barrier(0)
; template <class Epi, class Sched>
; __device__ __forceinline__ void gemm_phase(LAS unsigned char* lds_in, const int lda, const int ldb, const Sched& S, const Epi& E, const int WID) {
;     ...
;         for (int t = tb; t < te; t += 2) {
;             const bool last = (t == nt - 2);
;             const char* a1 = cA + (size_t)(t + 1) * kstep;
;             const char* a2 = last ? nA : cA + (size_t)(t + 2) * kstep; const char* b2 = last ? nB : cB + (size_t)(t + 2) * kstep;
;             const char* a3 = a2 + kstep; const char* b3 = b2 + kstep;
;             PG8_LDB(B0, 0, 0); PG8_SCHED; PG8_LDA(At, 0, 0); PG8_STAGE(PG8_SA(1, 1), a1 + hstepA, voffA);
;             PG8_WAIT_L(8); PG8_BAR; PG8_WAIT_L(0); PG8_MMA(0, 0, At, B0); PG8_BAR; PG8_SCHED;
;             PG8_LDB(B1, 0, 1); PG8_STAGE(PG8_SB(0, 0), b2, voffB);
;             PG8_BAR; PG8_WAIT_L(0); PG8_MMA(0, 1, At, B1); PG8_BAR;
;             PG8_LDA(At, 0, 1); PG8_STAGE(PG8_SA(0, 0), a2, voffA);
;             PG8_BAR; PG8_WAIT_L(0); PG8_MMA(1, 0, At, B0); PG8_BAR; PG8_SCHED;
.LBB0_1040:
	v_add_u32_e32 v142, s3, v174
	ds_read_b128 v[130:133], v142
	ds_read_b128 v[134:137], v142 offset:1024
	ds_read_b128 v[138:141], v142 offset:2048
	ds_read_b128 v[142:145], v142 offset:3072
	s_add_u32 s20, s18, 0xfff80080
	s_addc_u32 s21, s19, -1
	s_cmp_eq_u32 s70, s32
	s_cselect_b32 s23, s13, s21
	s_cselect_b32 s22, s12, s20
	s_cselect_b32 s21, s15, s11
	s_cselect_b32 s20, s14, s1
	s_add_i32 m0, s46, 0xc000
	ds_read_b128 v[158:161], v176
	ds_read_b128 v[162:165], v176 offset:1024
	ds_read_b128 v[166:169], v176 offset:2048
	ds_read_b128 v[170:173], v176 offset:3072
	ds_read_b128 v[178:181], v176 offset:4096
	ds_read_b128 v[182:185], v176 offset:5120
	ds_read_b128 v[186:189], v176 offset:6144
	ds_read_b128 v[190:193], v176 offset:7168
	global_load_lds_dwordx4 v154, s[18:19]
	s_add_i32 m0, s46, 0xe000
	s_nop 0
	global_load_lds_dwordx4 v156, s[18:19]
	s_waitcnt lgkmcnt(8)
	s_barrier
	s_waitcnt lgkmcnt(0)
	s_setprio 1
	s_waitcnt lgkmcnt(0)
	v_mfma_f32_16x16x32_bf16 v[126:129], v[130:133], v[158:161], v[126:129]
	v_mfma_f32_16x16x32_bf16 v[122:125], v[138:141], v[158:161], v[122:125]
	v_mfma_f32_16x16x32_bf16 v[118:121], v[130:133], v[166:169], v[118:121]
	v_mfma_f32_16x16x32_bf16 v[114:117], v[138:141], v[166:169], v[114:117]
	v_mfma_f32_16x16x32_bf16 v[110:113], v[130:133], v[178:181], v[110:113]
	v_mfma_f32_16x16x32_bf16 v[106:109], v[138:141], v[178:181], v[106:109]
	v_mfma_f32_16x16x32_bf16 v[102:105], v[130:133], v[186:189], v[102:105]
	v_mfma_f32_16x16x32_bf16 v[98:101], v[138:141], v[186:189], v[98:101]
	v_mfma_f32_16x16x32_bf16 v[126:129], v[134:137], v[162:165], v[126:129]
	v_mfma_f32_16x16x32_bf16 v[122:125], v[142:145], v[162:165], v[122:125]
	v_mfma_f32_16x16x32_bf16 v[118:121], v[134:137], v[170:173], v[118:121]
	v_mfma_f32_16x16x32_bf16 v[114:117], v[142:145], v[170:173], v[114:117]
	v_mfma_f32_16x16x32_bf16 v[110:113], v[134:137], v[182:185], v[110:113]
	v_mfma_f32_16x16x32_bf16 v[106:109], v[142:145], v[182:185], v[106:109]
	v_mfma_f32_16x16x32_bf16 v[102:105], v[134:137], v[190:193], v[102:105]
	v_mfma_f32_16x16x32_bf16 v[98:101], v[142:145], v[190:193], v[98:101]
	s_setprio 0
	s_barrier
	s_mov_b32 m0, s17
	v_add_u32_e32 v177, s48, v174
	ds_read_b128 v[194:197], v177
	ds_read_b128 v[198:201], v177 offset:1024
	ds_read_b128 v[202:205], v177 offset:2048
	ds_read_b128 v[206:209], v177 offset:3072
	global_load_lds_dwordx4 v148, s[20:21]
	s_mov_b32 m0, s35
	s_nop 0
	global_load_lds_dwordx4 v152, s[20:21]
	s_barrier
	s_waitcnt lgkmcnt(0)
	s_setprio 1
	s_waitcnt lgkmcnt(0)
	v_mfma_f32_16x16x32_bf16 v[62:65], v[194:197], v[158:161], v[62:65]
	v_mfma_f32_16x16x32_bf16 v[58:61], v[202:205], v[158:161], v[58:61]
	v_mfma_f32_16x16x32_bf16 v[54:57], v[194:197], v[166:169], v[54:57]
	v_mfma_f32_16x16x32_bf16 v[50:53], v[202:205], v[166:169], v[50:53]
	v_mfma_f32_16x16x32_bf16 v[46:49], v[194:197], v[178:181], v[46:49]
	v_mfma_f32_16x16x32_bf16 v[42:45], v[202:205], v[178:181], v[42:45]
	v_mfma_f32_16x16x32_bf16 v[38:41], v[194:197], v[186:189], v[38:41]
	v_mfma_f32_16x16x32_bf16 v[34:37], v[202:205], v[186:189], v[34:37]
	v_mfma_f32_16x16x32_bf16 v[62:65], v[198:201], v[162:165], v[62:65]
	v_mfma_f32_16x16x32_bf16 v[58:61], v[206:209], v[162:165], v[58:61]
	v_mfma_f32_16x16x32_bf16 v[54:57], v[198:201], v[170:173], v[54:57]
	v_mfma_f32_16x16x32_bf16 v[50:53], v[206:209], v[170:173], v[50:53]
	v_mfma_f32_16x16x32_bf16 v[46:49], v[198:201], v[182:185], v[46:49]
	v_mfma_f32_16x16x32_bf16 v[42:45], v[206:209], v[182:185], v[42:45]
	v_mfma_f32_16x16x32_bf16 v[38:41], v[198:201], v[190:193], v[38:41]
	v_mfma_f32_16x16x32_bf16 v[34:37], v[206:209], v[190:193], v[34:37]
	s_setprio 0
	s_mov_b32 m0, s46
	s_barrier
	ds_read_b128 v[158:161], v176 offset:16384
	ds_read_b128 v[162:165], v176 offset:17408
	ds_read_b128 v[166:169], v176 offset:18432
	ds_read_b128 v[170:173], v176 offset:19456
	ds_read_b128 v[178:181], v176 offset:20480
	ds_read_b128 v[182:185], v176 offset:21504
	ds_read_b128 v[186:189], v176 offset:22528
	ds_read_b128 v[190:193], v176 offset:23552
	global_load_lds_dwordx4 v146, s[22:23]
	s_mov_b32 m0, s47
	s_nop 0
	global_load_lds_dwordx4 v150, s[22:23]
	s_barrier
	s_waitcnt lgkmcnt(0)
	s_setprio 1
	s_waitcnt lgkmcnt(0)
	v_mfma_f32_16x16x32_bf16 v[94:97], v[130:133], v[158:161], v[94:97]
	v_mfma_f32_16x16x32_bf16 v[90:93], v[138:141], v[158:161], v[90:93]
	v_mfma_f32_16x16x32_bf16 v[86:89], v[130:133], v[166:169], v[86:89]
	v_mfma_f32_16x16x32_bf16 v[82:85], v[138:141], v[166:169], v[82:85]
	v_mfma_f32_16x16x32_bf16 v[78:81], v[130:133], v[178:181], v[78:81]
	v_mfma_f32_16x16x32_bf16 v[74:77], v[138:141], v[178:181], v[74:77]
	v_mfma_f32_16x16x32_bf16 v[70:73], v[130:133], v[186:189], v[70:73]
	v_mfma_f32_16x16x32_bf16 v[66:69], v[138:141], v[186:189], v[66:69]
	v_mfma_f32_16x16x32_bf16 v[94:97], v[134:137], v[162:165], v[94:97]
	v_mfma_f32_16x16x32_bf16 v[90:93], v[142:145], v[162:165], v[90:93]
	v_mfma_f32_16x16x32_bf16 v[86:89], v[134:137], v[170:173], v[86:89]
	v_mfma_f32_16x16x32_bf16 v[82:85], v[142:145], v[170:173], v[82:85]
	v_mfma_f32_16x16x32_bf16 v[78:81], v[134:137], v[182:185], v[78:81]
	v_mfma_f32_16x16x32_bf16 v[74:77], v[142:145], v[182:185], v[74:77]
	v_mfma_f32_16x16x32_bf16 v[70:73], v[134:137], v[190:193], v[70:73]
	v_mfma_f32_16x16x32_bf16 v[66:69], v[142:145], v[190:193], v[66:69]
	s_setprio 0
	s_barrier
	s_add_u32 s96, s20, 0x80000
	s_addc_u32 s97, s21, 0
	s_mov_b32 m0, s49
	s_nop 0
	global_load_lds_dwordx4 v148, s[96:97]
	s_mov_b32 m0, s50
	s_nop 0
	global_load_lds_dwordx4 v152, s[96:97]
	s_waitcnt vmcnt(6)
	s_barrier
; #define PG8_STAGE(bufoff, gbase, voff) do { _Pragma("unroll") for (int _i = 0; _i < 2; ++_i) \
;         __builtin_amdgcn_global_load_lds((const unsigned*)((const char*)(gbase) + (voff)[_i]), (LAS unsigned*)(lds + (bufoff) + ldsw + _i * 8192), 16, 0, 0); } while (0)
; #define PG8_LDA(dst, b, h) do { _Pragma("unroll") for (int m = 0; m < 4; ++m) _Pragma("unroll") for (int k = 0; k < 2; ++k) dst[m][k] = *(const LAS bf16x8*)(lds + PG8_SA(b, h) + aoff + m * 2048 + k * 1024); } while (0)
; #define PG8_LDB(dst, b, h) do { _Pragma("unroll") for (int n = 0; n < 2; ++n) _Pragma("unroll") for (int k = 0; k < 2; ++k) dst[n][k] = *(const LAS bf16x8*)(lds + PG8_SB(b, h) + boff + n * 2048 + k * 1024); } while (0)
; #define PG8_MMA(ai, bj, At, Bt) do { __builtin_amdgcn_s_setprio(1); _Pragma("unroll") for (int m = 0; m < 4; ++m) _Pragma("unroll") for (int n = 0; n < 2; ++n) _Pragma("unroll") for (int k = 0; k < 2; ++k) \
;         acc[ai][bj][m][n] = __builtin_amdgcn_mfma_f32_16x16x32_bf16(Bt[n][k], At[m][k], acc[ai][bj][m][n], 0, 0, 0); __builtin_amdgcn_s_setprio(0); } while (0)
; #define PG8_WAIT_V(n) asm volatile("s_waitcnt vmcnt(" #n ")" ::: "memory")
; #define PG8_WAIT_L(n) asm volatile("s_waitcnt lgkmcnt(" #n ")" ::: "memory")
; #define PG8_BAR __builtin_amdgcn_s_barrier()
; #define PG8_SCHED __builtin_amdgcn_sched_barrier(0)
; template <class Epi, class Sched>
; __device__ __forceinline__ void gemm_phase(LAS unsigned char* lds_in, const int lda, const int ldb, const Sched& S, const Epi& E, const int WID) {
;     ...
;             PG8_BAR; PG8_WAIT_L(0); PG8_MMA(1, 0, At, B0); PG8_BAR; PG8_SCHED;
;             PG8_STAGE(PG8_SB(0, 1), b2 + hstepB, voffB);
;             PG8_WAIT_V(6); PG8_BAR; PG8_MMA(1, 1, At, B1); PG8_BAR;
;             PG8_LDB(B0, 1, 0); PG8_SCHED; PG8_LDA(At, 1, 0); PG8_STAGE(PG8_SA(0, 1), a2 + hstepA, voffA);
;             PG8_WAIT_L(8); PG8_BAR; PG8_WAIT_L(0); PG8_MMA(0, 0, At, B0); PG8_BAR; PG8_SCHED;
;             PG8_LDB(B1, 1, 1); PG8_STAGE(PG8_SB(1, 0), b3, voffB);
	s_setprio 1
	v_mfma_f32_16x16x32_bf16 v[30:33], v[194:197], v[158:161], v[30:33]
	v_mfma_f32_16x16x32_bf16 v[26:29], v[202:205], v[158:161], v[26:29]
	v_mfma_f32_16x16x32_bf16 v[22:25], v[194:197], v[166:169], v[22:25]
	v_mfma_f32_16x16x32_bf16 v[18:21], v[202:205], v[166:169], v[18:21]
	v_mfma_f32_16x16x32_bf16 v[14:17], v[194:197], v[178:181], v[14:17]
	v_mfma_f32_16x16x32_bf16 v[10:13], v[202:205], v[178:181], v[10:13]
	v_mfma_f32_16x16x32_bf16 v[6:9], v[194:197], v[186:189], v[6:9]
	v_mfma_f32_16x16x32_bf16 v[2:5], v[202:205], v[186:189], v[2:5]
	v_mfma_f32_16x16x32_bf16 v[30:33], v[198:201], v[162:165], v[30:33]
	v_mfma_f32_16x16x32_bf16 v[26:29], v[206:209], v[162:165], v[26:29]
	v_mfma_f32_16x16x32_bf16 v[22:25], v[198:201], v[170:173], v[22:25]
	v_mfma_f32_16x16x32_bf16 v[18:21], v[206:209], v[170:173], v[18:21]
	v_mfma_f32_16x16x32_bf16 v[14:17], v[198:201], v[182:185], v[14:17]
	v_mfma_f32_16x16x32_bf16 v[10:13], v[206:209], v[182:185], v[10:13]
	v_mfma_f32_16x16x32_bf16 v[6:9], v[198:201], v[190:193], v[6:9]
	v_mfma_f32_16x16x32_bf16 v[2:5], v[206:209], v[190:193], v[2:5]
	s_setprio 0
	v_add_u32_e32 v142, s78, v174
	s_barrier
	ds_read_b128 v[130:133], v142
	ds_read_b128 v[134:137], v142 offset:1024
	ds_read_b128 v[138:141], v142 offset:2048
	ds_read_b128 v[142:145], v142 offset:3072
	s_add_u32 s22, s22, 0x80000
	s_addc_u32 s23, s23, 0
	s_mov_b32 m0, s51
	ds_read_b128 v[158:161], v176 offset:32768
	ds_read_b128 v[162:165], v176 offset:33792
	ds_read_b128 v[166:169], v176 offset:34816
	ds_read_b128 v[170:173], v176 offset:35840
	ds_read_b128 v[178:181], v176 offset:36864
	ds_read_b128 v[182:185], v176 offset:37888
	ds_read_b128 v[186:189], v176 offset:38912
	ds_read_b128 v[190:193], v176 offset:39936
	global_load_lds_dwordx4 v146, s[22:23]
	s_mov_b32 m0, s65
	s_nop 0
	global_load_lds_dwordx4 v150, s[22:23]
	s_waitcnt lgkmcnt(8)
	s_barrier
	s_waitcnt lgkmcnt(0)
	s_setprio 1
	s_waitcnt lgkmcnt(0)
	v_mfma_f32_16x16x32_bf16 v[126:129], v[130:133], v[158:161], v[126:129]
	v_mfma_f32_16x16x32_bf16 v[122:125], v[138:141], v[158:161], v[122:125]
	v_mfma_f32_16x16x32_bf16 v[118:121], v[130:133], v[166:169], v[118:121]
	v_mfma_f32_16x16x32_bf16 v[114:117], v[138:141], v[166:169], v[114:117]
	v_mfma_f32_16x16x32_bf16 v[110:113], v[130:133], v[178:181], v[110:113]
	v_mfma_f32_16x16x32_bf16 v[106:109], v[138:141], v[178:181], v[106:109]
	v_mfma_f32_16x16x32_bf16 v[102:105], v[130:133], v[186:189], v[102:105]
	v_mfma_f32_16x16x32_bf16 v[98:101], v[138:141], v[186:189], v[98:101]
	v_mfma_f32_16x16x32_bf16 v[126:129], v[134:137], v[162:165], v[126:129]
	v_mfma_f32_16x16x32_bf16 v[122:125], v[142:145], v[162:165], v[122:125]
	v_mfma_f32_16x16x32_bf16 v[118:121], v[134:137], v[170:173], v[118:121]
	v_mfma_f32_16x16x32_bf16 v[114:117], v[142:145], v[170:173], v[114:117]
	v_mfma_f32_16x16x32_bf16 v[110:113], v[134:137], v[182:185], v[110:113]
	v_mfma_f32_16x16x32_bf16 v[106:109], v[142:145], v[182:185], v[106:109]
	v_mfma_f32_16x16x32_bf16 v[102:105], v[134:137], v[190:193], v[102:105]
	v_mfma_f32_16x16x32_bf16 v[98:101], v[142:145], v[190:193], v[98:101]
	s_setprio 0
	s_barrier
	s_mov_b32 m0, s79
	v_add_u32_e32 v177, s90, v174
	s_add_u32 s100, s20, 0x80
	s_addc_u32 s101, s21, 0
	ds_read_b128 v[194:197], v177
	ds_read_b128 v[198:201], v177 offset:1024
	ds_read_b128 v[202:205], v177 offset:2048
	ds_read_b128 v[206:209], v177 offset:3072
	global_load_lds_dwordx4 v148, s[100:101]
	s_add_u32 s100, s20, 0x80
	s_addc_u32 s101, s21, 0
	s_mov_b32 m0, s2
	s_nop 0
	global_load_lds_dwordx4 v152, s[100:101]
	s_barrier
	s_waitcnt lgkmcnt(0)
	s_setprio 1
	s_waitcnt lgkmcnt(0)
	v_mfma_f32_16x16x32_bf16 v[62:65], v[194:197], v[158:161], v[62:65]
	v_mfma_f32_16x16x32_bf16 v[58:61], v[202:205], v[158:161], v[58:61]
	v_mfma_f32_16x16x32_bf16 v[54:57], v[194:197], v[166:169], v[54:57]
	v_mfma_f32_16x16x32_bf16 v[50:53], v[202:205], v[166:169], v[50:53]
	v_mfma_f32_16x16x32_bf16 v[46:49], v[194:197], v[178:181], v[46:49]
	v_mfma_f32_16x16x32_bf16 v[42:45], v[202:205], v[178:181], v[42:45]
	v_mfma_f32_16x16x32_bf16 v[38:41], v[194:197], v[186:189], v[38:41]
	v_mfma_f32_16x16x32_bf16 v[34:37], v[202:205], v[186:189], v[34:37]
	v_mfma_f32_16x16x32_bf16 v[62:65], v[198:201], v[162:165], v[62:65]
	v_mfma_f32_16x16x32_bf16 v[58:61], v[206:209], v[162:165], v[58:61]
	v_mfma_f32_16x16x32_bf16 v[54:57], v[198:201], v[170:173], v[54:57]
	v_mfma_f32_16x16x32_bf16 v[50:53], v[206:209], v[170:173], v[50:53]
	v_mfma_f32_16x16x32_bf16 v[46:49], v[198:201], v[182:185], v[46:49]
	v_mfma_f32_16x16x32_bf16 v[42:45], v[206:209], v[182:185], v[42:45]
	v_mfma_f32_16x16x32_bf16 v[38:41], v[198:201], v[190:193], v[38:41]
	v_mfma_f32_16x16x32_bf16 v[34:37], v[206:209], v[190:193], v[34:37]
	s_setprio 0
	s_mov_b32 m0, s4
	s_add_u32 s100, s22, 0xfff80080
	s_addc_u32 s101, s23, -1
	s_barrier
	ds_read_b128 v[158:161], v176 offset:49152
	ds_read_b128 v[162:165], v176 offset:50176
	ds_read_b128 v[166:169], v176 offset:51200
	ds_read_b128 v[170:173], v176 offset:52224
	ds_read_b128 v[178:181], v176 offset:53248
	ds_read_b128 v[182:185], v176 offset:54272
	ds_read_b128 v[186:189], v176 offset:55296
	ds_read_b128 v[190:193], v176 offset:56320
	global_load_lds_dwordx4 v146, s[100:101]
	s_add_u32 s100, s22, 0xfff80080
	s_addc_u32 s101, s23, -1
	s_mov_b32 m0, s5
	s_nop 0
	global_load_lds_dwordx4 v150, s[100:101]
	s_barrier
; #define PG8_STAGE(bufoff, gbase, voff) do { _Pragma("unroll") for (int _i = 0; _i < 2; ++_i) \
;         __builtin_amdgcn_global_load_lds((const unsigned*)((const char*)(gbase) + (voff)[_i]), (LAS unsigned*)(lds + (bufoff) + ldsw + _i * 8192), 16, 0, 0); } while (0)
; #define PG8_MMA(ai, bj, At, Bt) do { __builtin_amdgcn_s_setprio(1); _Pragma("unroll") for (int m = 0; m < 4; ++m) _Pragma("unroll") for (int n = 0; n < 2; ++n) _Pragma("unroll") for (int k = 0; k < 2; ++k) \
;         acc[ai][bj][m][n] = __builtin_amdgcn_mfma_f32_16x16x32_bf16(Bt[n][k], At[m][k], acc[ai][bj][m][n], 0, 0, 0); __builtin_amdgcn_s_setprio(0); } while (0)
; #define PG8_WAIT_V(n) asm volatile("s_waitcnt vmcnt(" #n ")" ::: "memory")
; #define PG8_WAIT_L(n) asm volatile("s_waitcnt lgkmcnt(" #n ")" ::: "memory")
; #define PG8_BAR __builtin_amdgcn_s_barrier()
; #define PG8_SCHED __builtin_amdgcn_sched_barrier(0)
; template <class Epi, class Sched>
; __device__ __forceinline__ void gemm_phase(LAS unsigned char* lds_in, const int lda, const int ldb, const Sched& S, const Epi& E, const int WID) {
;     ...
;             PG8_BAR; PG8_WAIT_L(0); PG8_MMA(1, 0, At, B0); PG8_BAR; PG8_SCHED;
;             PG8_STAGE(PG8_SB(1, 1), b3 + hstepB, voffB);
;             PG8_WAIT_V(6); PG8_BAR; PG8_MMA(1, 1, At, B1); PG8_BAR;
;         }
;         }
;         E(acc, cur, wr, wc, fr, fq);
	s_waitcnt lgkmcnt(0)
	s_setprio 1
	s_waitcnt lgkmcnt(0)
	v_mfma_f32_16x16x32_bf16 v[94:97], v[130:133], v[158:161], v[94:97]
	v_mfma_f32_16x16x32_bf16 v[90:93], v[138:141], v[158:161], v[90:93]
	v_mfma_f32_16x16x32_bf16 v[86:89], v[130:133], v[166:169], v[86:89]
	v_mfma_f32_16x16x32_bf16 v[82:85], v[138:141], v[166:169], v[82:85]
	v_mfma_f32_16x16x32_bf16 v[78:81], v[130:133], v[178:181], v[78:81]
	v_mfma_f32_16x16x32_bf16 v[74:77], v[138:141], v[178:181], v[74:77]
	v_mfma_f32_16x16x32_bf16 v[70:73], v[130:133], v[186:189], v[70:73]
	v_mfma_f32_16x16x32_bf16 v[66:69], v[138:141], v[186:189], v[66:69]
	v_mfma_f32_16x16x32_bf16 v[94:97], v[134:137], v[162:165], v[94:97]
	v_mfma_f32_16x16x32_bf16 v[90:93], v[142:145], v[162:165], v[90:93]
	v_mfma_f32_16x16x32_bf16 v[86:89], v[134:137], v[170:173], v[86:89]
	v_mfma_f32_16x16x32_bf16 v[82:85], v[142:145], v[170:173], v[82:85]
	v_mfma_f32_16x16x32_bf16 v[78:81], v[134:137], v[182:185], v[78:81]
	v_mfma_f32_16x16x32_bf16 v[74:77], v[142:145], v[182:185], v[74:77]
	v_mfma_f32_16x16x32_bf16 v[70:73], v[134:137], v[190:193], v[70:73]
	v_mfma_f32_16x16x32_bf16 v[66:69], v[142:145], v[190:193], v[66:69]
	s_setprio 0
	s_barrier
	s_add_u32 s20, s20, 0x80080
	s_addc_u32 s21, s21, 0
	s_mov_b32 m0, s91
	s_nop 0
	global_load_lds_dwordx4 v148, s[20:21]
	s_mov_b32 m0, s92
	s_nop 0
	global_load_lds_dwordx4 v152, s[20:21]
	s_waitcnt vmcnt(6)
	s_barrier
	s_setprio 1
	v_mfma_f32_16x16x32_bf16 v[30:33], v[194:197], v[158:161], v[30:33]
	v_mfma_f32_16x16x32_bf16 v[26:29], v[202:205], v[158:161], v[26:29]
	v_mfma_f32_16x16x32_bf16 v[22:25], v[194:197], v[166:169], v[22:25]
	v_mfma_f32_16x16x32_bf16 v[18:21], v[202:205], v[166:169], v[18:21]
	v_mfma_f32_16x16x32_bf16 v[14:17], v[194:197], v[178:181], v[14:17]
	v_mfma_f32_16x16x32_bf16 v[10:13], v[202:205], v[178:181], v[10:13]
	v_mfma_f32_16x16x32_bf16 v[6:9], v[194:197], v[186:189], v[6:9]
	v_mfma_f32_16x16x32_bf16 v[2:5], v[202:205], v[186:189], v[2:5]
	v_mfma_f32_16x16x32_bf16 v[30:33], v[198:201], v[162:165], v[30:33]
	v_mfma_f32_16x16x32_bf16 v[26:29], v[206:209], v[162:165], v[26:29]
	v_mfma_f32_16x16x32_bf16 v[22:25], v[198:201], v[170:173], v[22:25]
	v_mfma_f32_16x16x32_bf16 v[18:21], v[206:209], v[170:173], v[18:21]
	v_mfma_f32_16x16x32_bf16 v[14:17], v[198:201], v[182:185], v[14:17]
	v_mfma_f32_16x16x32_bf16 v[10:13], v[206:209], v[182:185], v[10:13]
	v_mfma_f32_16x16x32_bf16 v[6:9], v[198:201], v[190:193], v[6:9]
	v_mfma_f32_16x16x32_bf16 v[2:5], v[206:209], v[190:193], v[2:5]
	s_setprio 0
	s_add_i32 s70, s70, 2
	s_add_u32 s18, s18, 0x100
	s_addc_u32 s19, s19, 0
	s_add_u32 s1, s1, 0x100
	s_addc_u32 s11, s11, 0
	s_cmp_gt_u32 s70, s32
	s_barrier
	s_cbranch_scc0 .LBB0_1040
	s_lshl_b32 s11, s16, 8
	v_lshl_add_u32 v160, s0, 8, v1
	v_or_b32_e32 v158, s11, v175
	s_cmp_lg_u32 s94, 0
	v_ashrrev_i32_e32 v159, 31, v158
	v_ashrrev_i32_e32 v161, 31, v160
	s_cbranch_scc0 .LBB0_1107
	s_cmp_eq_u32 s99, 0
	s_cbranch_scc1 .Lks_go
	v_readlane_b32 vcc_lo, v255, 1
	v_readlane_b32 s22, v255, 3
	v_lshrrev_b32_e32 v130, 6, v1
	v_lshrrev_b32_e32 v131, 5, v175
	v_and_b32_e32 v131, 3, v131
	v_lshl_add_u32 v131, v130, 2, v131
	v_lshlrev_b32_e32 v130, 15, v131
	v_lshl_add_u32 v162, v248, 4, v130
	s_and_b32 vcc_lo, vcc_lo, 0x7f
	s_or_b32 s22, s22, 0x5a5a0000
	s_lshl_b32 s18, vcc_lo, 18
	s_add_u32 s18, s18, 0x1c000000
	s_add_u32 s18, s30, s18
	s_addc_u32 s19, s31, 0
	s_lshl_b32 s20, vcc_lo, 6
	s_add_u32 s20, s20, 0x1e000000
	s_add_u32 s20, s30, s20
	s_addc_u32 s21, s31, 0
	v_add_u32_e32 v163, 0x1000, v162
	v_add_u32_e32 v164, 0x2000, v162
	v_add_u32_e32 v165, 0x3000, v162
	v_add_u32_e32 v166, 0x4000, v162
	v_add_u32_e32 v167, 0x5000, v162
	v_add_u32_e32 v168, 0x6000, v162
	v_add_u32_e32 v169, 0x7000, v162
	v_lshlrev_b32_e32 v170, 2, v131
	s_cmp_eq_u32 s99, 2
	s_cbranch_scc1 .Lks_writer
	s_mov_b32 s23, 0
.Lks_spin:
	global_load_dword v132, v170, s[20:21] sc0 sc1
	s_waitcnt vmcnt(0)
	v_readfirstlane_b32 vcc_lo, v132
	s_cmp_eq_u32 vcc_lo, s22
	s_cbranch_scc1 .Lks_got
	s_add_i32 s23, s23, 1
	s_cmp_lt_u32 s23, 0x8000
	s_cbranch_scc0 .Lks_got
	s_sleep 4
	s_branch .Lks_spin
.Lks_got:
	global_load_dwordx4 v[178:181], v162, s[18:19] offset:0 sc0 sc1
	global_load_dwordx4 v[182:185], v162, s[18:19] offset:1024 sc0 sc1
	global_load_dwordx4 v[186:189], v162, s[18:19] offset:2048 sc0 sc1
	global_load_dwordx4 v[190:193], v162, s[18:19] offset:3072 sc0 sc1
	global_load_dwordx4 v[194:197], v163, s[18:19] offset:0 sc0 sc1
	global_load_dwordx4 v[198:201], v163, s[18:19] offset:1024 sc0 sc1
	global_load_dwordx4 v[202:205], v163, s[18:19] offset:2048 sc0 sc1
	global_load_dwordx4 v[206:209], v163, s[18:19] offset:3072 sc0 sc1
	s_waitcnt vmcnt(0)
	v_pk_add_f32 v[2:3], v[2:3], v[178:179]
	v_pk_add_f32 v[4:5], v[4:5], v[180:181]
	v_pk_add_f32 v[6:7], v[6:7], v[182:183]
	v_pk_add_f32 v[8:9], v[8:9], v[184:185]
	v_pk_add_f32 v[10:11], v[10:11], v[186:187]
	v_pk_add_f32 v[12:13], v[12:13], v[188:189]
	v_pk_add_f32 v[14:15], v[14:15], v[190:191]
	v_pk_add_f32 v[16:17], v[16:17], v[192:193]
	v_pk_add_f32 v[18:19], v[18:19], v[194:195]
	v_pk_add_f32 v[20:21], v[20:21], v[196:197]
	v_pk_add_f32 v[22:23], v[22:23], v[198:199]
	v_pk_add_f32 v[24:25], v[24:25], v[200:201]
	v_pk_add_f32 v[26:27], v[26:27], v[202:203]
	v_pk_add_f32 v[28:29], v[28:29], v[204:205]
	v_pk_add_f32 v[30:31], v[30:31], v[206:207]
	v_pk_add_f32 v[32:33], v[32:33], v[208:209]
	global_load_dwordx4 v[178:181], v164, s[18:19] offset:0 sc0 sc1
	global_load_dwordx4 v[182:185], v164, s[18:19] offset:1024 sc0 sc1
	global_load_dwordx4 v[186:189], v164, s[18:19] offset:2048 sc0 sc1
	global_load_dwordx4 v[190:193], v164, s[18:19] offset:3072 sc0 sc1
	global_load_dwordx4 v[194:197], v165, s[18:19] offset:0 sc0 sc1
	global_load_dwordx4 v[198:201], v165, s[18:19] offset:1024 sc0 sc1
	global_load_dwordx4 v[202:205], v165, s[18:19] offset:2048 sc0 sc1
	global_load_dwordx4 v[206:209], v165, s[18:19] offset:3072 sc0 sc1
	s_waitcnt vmcnt(0)
; __device__ __forceinline__ float rstd_of(float ss) { return rsqrtf(ss * (1.0f / DM) + EPS); }
; __device__ __forceinline__ u32x4 pack8(const f32x4 a, const f32x4 b) { u32x4 w; w.x = cvt_pk_bf16(a[0], a[1]); w.y = cvt_pk_bf16(a[2], a[3]); w.z = cvt_pk_bf16(b[0], b[1]); w.w = cvt_pk_bf16(b[2], b[3]); return w; }
;     __device__ __forceinline__ void operator()(const AccT& acc, const Unit& u, int wr, int wc, int fr, int fq) const {
;     ...
;             const bool scat = sample && u.pm < 2;
;             f32x4 rs0[2], rs1[2];
; #pragma unroll
;             for (int bj = 0; bj < 2; ++bj) { const f32x4 a = *(const f32x4*)(SS + col0 + bj * 128), b = *(const f32x4*)(SS + col0 + bj * 128 + 4);
; #pragma unroll
;                 for (int j = 0; j < 4; ++j) { rs0[bj][j] = rstd_of(a[j]); rs1[bj][j] = rstd_of(b[j]); } }
; #pragma unroll
;             for (int ai = 0; ai < 2; ++ai)
; #pragma unroll
;                 for (int m = 0; m < 4; ++m) {
;                     bf16_t* rp = TT + (size_t)(row0 + ai * 128 + m * 16) * CH;
; #pragma unroll
;                     for (int bj = 0; bj < 2; ++bj) {
;                         const u32x4 w = pack8(acc[ai][bj][m][0] * rs0[bj], acc[ai][bj][m][1] * rs1[bj]);
;                         const int tok = col0 + bj * 128;
;                         if (!scat) *(u32x4*)(rp + tok) = w;
	v_pk_add_f32 v[34:35], v[34:35], v[178:179]
	v_pk_add_f32 v[36:37], v[36:37], v[180:181]
	v_pk_add_f32 v[38:39], v[38:39], v[182:183]
	v_pk_add_f32 v[40:41], v[40:41], v[184:185]
	v_pk_add_f32 v[42:43], v[42:43], v[186:187]
	v_pk_add_f32 v[44:45], v[44:45], v[188:189]
	v_pk_add_f32 v[46:47], v[46:47], v[190:191]
	v_pk_add_f32 v[48:49], v[48:49], v[192:193]
	v_pk_add_f32 v[50:51], v[50:51], v[194:195]
	v_pk_add_f32 v[52:53], v[52:53], v[196:197]
	v_pk_add_f32 v[54:55], v[54:55], v[198:199]
	v_pk_add_f32 v[56:57], v[56:57], v[200:201]
	v_pk_add_f32 v[58:59], v[58:59], v[202:203]
	v_pk_add_f32 v[60:61], v[60:61], v[204:205]
	v_pk_add_f32 v[62:63], v[62:63], v[206:207]
	v_pk_add_f32 v[64:65], v[64:65], v[208:209]
	global_load_dwordx4 v[178:181], v166, s[18:19] offset:0 sc0 sc1
	global_load_dwordx4 v[182:185], v166, s[18:19] offset:1024 sc0 sc1
	global_load_dwordx4 v[186:189], v166, s[18:19] offset:2048 sc0 sc1
	global_load_dwordx4 v[190:193], v166, s[18:19] offset:3072 sc0 sc1
	global_load_dwordx4 v[194:197], v167, s[18:19] offset:0 sc0 sc1
	global_load_dwordx4 v[198:201], v167, s[18:19] offset:1024 sc0 sc1
	global_load_dwordx4 v[202:205], v167, s[18:19] offset:2048 sc0 sc1
	global_load_dwordx4 v[206:209], v167, s[18:19] offset:3072 sc0 sc1
	s_waitcnt vmcnt(0)
	v_pk_add_f32 v[66:67], v[66:67], v[178:179]
	v_pk_add_f32 v[68:69], v[68:69], v[180:181]
	v_pk_add_f32 v[70:71], v[70:71], v[182:183]
	v_pk_add_f32 v[72:73], v[72:73], v[184:185]
	v_pk_add_f32 v[74:75], v[74:75], v[186:187]
	v_pk_add_f32 v[76:77], v[76:77], v[188:189]
	v_pk_add_f32 v[78:79], v[78:79], v[190:191]
	v_pk_add_f32 v[80:81], v[80:81], v[192:193]
	v_pk_add_f32 v[82:83], v[82:83], v[194:195]
	v_pk_add_f32 v[84:85], v[84:85], v[196:197]
	v_pk_add_f32 v[86:87], v[86:87], v[198:199]
	v_pk_add_f32 v[88:89], v[88:89], v[200:201]
	v_pk_add_f32 v[90:91], v[90:91], v[202:203]
	v_pk_add_f32 v[92:93], v[92:93], v[204:205]
	v_pk_add_f32 v[94:95], v[94:95], v[206:207]
	v_pk_add_f32 v[96:97], v[96:97], v[208:209]
	global_load_dwordx4 v[178:181], v168, s[18:19] offset:0 sc0 sc1
	global_load_dwordx4 v[182:185], v168, s[18:19] offset:1024 sc0 sc1
	global_load_dwordx4 v[186:189], v168, s[18:19] offset:2048 sc0 sc1
	global_load_dwordx4 v[190:193], v168, s[18:19] offset:3072 sc0 sc1
	global_load_dwordx4 v[194:197], v169, s[18:19] offset:0 sc0 sc1
	global_load_dwordx4 v[198:201], v169, s[18:19] offset:1024 sc0 sc1
	global_load_dwordx4 v[202:205], v169, s[18:19] offset:2048 sc0 sc1
	global_load_dwordx4 v[206:209], v169, s[18:19] offset:3072 sc0 sc1
	s_waitcnt vmcnt(0)
	v_pk_add_f32 v[98:99], v[98:99], v[178:179]
	v_pk_add_f32 v[100:101], v[100:101], v[180:181]
	v_pk_add_f32 v[102:103], v[102:103], v[182:183]
	v_pk_add_f32 v[104:105], v[104:105], v[184:185]
	v_pk_add_f32 v[106:107], v[106:107], v[186:187]
	v_pk_add_f32 v[108:109], v[108:109], v[188:189]
	v_pk_add_f32 v[110:111], v[110:111], v[190:191]
	v_pk_add_f32 v[112:113], v[112:113], v[192:193]
	v_pk_add_f32 v[114:115], v[114:115], v[194:195]
	v_pk_add_f32 v[116:117], v[116:117], v[196:197]
	v_pk_add_f32 v[118:119], v[118:119], v[198:199]
	v_pk_add_f32 v[120:121], v[120:121], v[200:201]
	v_pk_add_f32 v[122:123], v[122:123], v[202:203]
	v_pk_add_f32 v[124:125], v[124:125], v[204:205]
	v_pk_add_f32 v[126:127], v[126:127], v[206:207]
	v_pk_add_f32 v[128:129], v[128:129], v[208:209]
.Lks_go:
	v_lshl_add_u64 v[134:135], v[158:159], 2, s[76:77]
	global_load_dwordx4 v[130:133], v[134:135], off offset:16
	global_load_dwordx4 v[136:139], v[134:135], off
	s_cmp_lt_i32 s0, 2
	s_mov_b32 s0, 0x358637bd
	v_mov_b64_e32 v[140:141], s[0:1]
	s_cselect_b64 s[18:19], -1, 0
	s_mov_b64 s[20:21], -1
	s_waitcnt vmcnt(0)
	v_pk_fma_f32 v[130:131], v[130:131], s[84:85], v[140:141] op_sel_hi:[1,0,0]
	v_pk_fma_f32 v[136:137], v[136:137], s[84:85], v[140:141] op_sel_hi:[1,0,0]
	s_nop 0
	v_mul_f32_e32 v142, 0x4b800000, v136
	v_cmp_gt_f32_e64 s[0:1], s38, v136
	v_cmp_gt_f32_e32 vcc, s38, v137
	s_nop 0
	v_cndmask_b32_e64 v136, v136, v142, s[0:1]
	v_mul_f32_e32 v142, 0x4b800000, v137
	v_cndmask_b32_e32 v137, v137, v142, vcc
	v_rsq_f32_e32 v136, v136
	v_rsq_f32_e32 v137, v137
	s_nop 0
	v_pk_mul_f32 v[142:143], v[136:137], s[88:89] op_sel_hi:[1,0]
	s_nop 0
	v_cndmask_b32_e64 v142, v136, v142, s[0:1]
	v_mul_f32_e32 v136, 0x4b800000, v130
	v_cmp_gt_f32_e64 s[0:1], s38, v130
	v_cndmask_b32_e32 v143, v137, v143, vcc
	v_cmp_gt_f32_e32 vcc, s38, v131
	v_cndmask_b32_e64 v130, v130, v136, s[0:1]
	v_mul_f32_e32 v136, 0x4b800000, v131
	v_cndmask_b32_e32 v131, v131, v136, vcc
	v_rsq_f32_e32 v130, v130
	v_rsq_f32_e32 v131, v131
	s_nop 0
	v_pk_mul_f32 v[136:137], v[130:131], s[88:89] op_sel_hi:[1,0]
	s_nop 0
	v_cndmask_b32_e32 v145, v131, v137, vcc
	v_cndmask_b32_e64 v144, v130, v136, s[0:1]
	v_pk_fma_f32 v[130:131], v[138:139], s[84:85], v[140:141] op_sel_hi:[1,0,0]
	v_lshlrev_b64 v[138:139], 15, v[160:161]
	v_mul_f32_e32 v136, 0x4b800000, v130
	v_cmp_gt_f32_e64 s[0:1], s38, v130
	v_cmp_gt_f32_e32 vcc, s38, v131
	v_lshl_add_u64 v[166:167], s[86:87], 0, v[138:139]
	v_cndmask_b32_e64 v130, v130, v136, s[0:1]
	v_mul_f32_e32 v136, 0x4b800000, v131
	v_cndmask_b32_e32 v131, v131, v136, vcc
	v_rsq_f32_e32 v130, v130
	v_rsq_f32_e32 v131, v131
	v_pk_mul_f32 v[138:139], v[126:127], v[142:143]
	v_pk_mul_f32 v[168:169], v[122:123], v[144:145]
	v_cvt_pk_bf16_f32 v138, v138, v139
	v_pk_mul_f32 v[136:137], v[130:131], s[88:89] op_sel_hi:[1,0]
	s_nop 0
	v_cndmask_b32_e32 v163, v131, v137, vcc
	v_cndmask_b32_e64 v162, v130, v136, s[0:1]
	v_pk_fma_f32 v[130:131], v[132:133], s[84:85], v[140:141] op_sel_hi:[1,0,0]
	v_pk_mul_f32 v[140:141], v[128:129], v[162:163]
	v_mul_f32_e32 v132, 0x4b800000, v130
	v_cmp_gt_f32_e64 s[0:1], s38, v130
	v_cmp_gt_f32_e32 vcc, s38, v131
	v_cvt_pk_bf16_f32 v139, v140, v141
	v_cvt_pk_bf16_f32 v140, v168, v169
	v_lshl_add_u64 v[168:169], v[158:159], 1, v[166:167]
	v_cndmask_b32_e64 v130, v130, v132, s[0:1]
	v_mul_f32_e32 v132, 0x4b800000, v131
	v_cndmask_b32_e32 v131, v131, v132, vcc
	v_rsq_f32_e32 v130, v130
	v_rsq_f32_e32 v131, v131
	s_nop 0
	v_pk_mul_f32 v[132:133], v[130:131], s[88:89] op_sel_hi:[1,0]
	s_nop 0
	v_cndmask_b32_e32 v165, v131, v133, vcc
	v_cndmask_b32_e64 v164, v130, v132, s[0:1]
	global_load_dwordx4 v[130:133], v[134:135], off offset:528
	s_nop 0
	global_load_dwordx4 v[134:137], v[134:135], off offset:512
	v_readlane_b32 s0, v255, 10
	v_readlane_b32 s1, v255, 11
	s_and_b64 s[0:1], s[0:1], s[18:19]
	s_and_b64 vcc, exec, s[0:1]
	v_pk_mul_f32 v[170:171], v[124:125], v[164:165]
	s_nop 0
	v_cvt_pk_bf16_f32 v141, v170, v171
	s_cbranch_vccnz .LBB0_1044
	s_mov_b64 s[20:21], 0
	global_store_dwordx4 v[168:169], v[138:141], off

; template <class Epi, class Sched>
; __device__ __forceinline__ void gemm_phase(LAS unsigned char* lds_in, const int lda, const int ldb, const Sched& S, const Epi& E, const int WID) {
;     ...
;         E(acc, cur, wr, wc, fr, fq);
;         if (!has_next) break;
.Lks_writer:
	global_store_dwordx4 v162, v[2:5], s[18:19] offset:0 sc0 sc1
	global_store_dwordx4 v162, v[6:9], s[18:19] offset:1024 sc0 sc1
	global_store_dwordx4 v162, v[10:13], s[18:19] offset:2048 sc0 sc1
	global_store_dwordx4 v162, v[14:17], s[18:19] offset:3072 sc0 sc1
	global_store_dwordx4 v163, v[18:21], s[18:19] offset:0 sc0 sc1
	global_store_dwordx4 v163, v[22:25], s[18:19] offset:1024 sc0 sc1
	global_store_dwordx4 v163, v[26:29], s[18:19] offset:2048 sc0 sc1
	global_store_dwordx4 v163, v[30:33], s[18:19] offset:3072 sc0 sc1
	global_store_dwordx4 v164, v[34:37], s[18:19] offset:0 sc0 sc1
	global_store_dwordx4 v164, v[38:41], s[18:19] offset:1024 sc0 sc1
	global_store_dwordx4 v164, v[42:45], s[18:19] offset:2048 sc0 sc1
	global_store_dwordx4 v164, v[46:49], s[18:19] offset:3072 sc0 sc1
	global_store_dwordx4 v165, v[50:53], s[18:19] offset:0 sc0 sc1
	global_store_dwordx4 v165, v[54:57], s[18:19] offset:1024 sc0 sc1
	global_store_dwordx4 v165, v[58:61], s[18:19] offset:2048 sc0 sc1
	global_store_dwordx4 v165, v[62:65], s[18:19] offset:3072 sc0 sc1
	global_store_dwordx4 v166, v[66:69], s[18:19] offset:0 sc0 sc1
	global_store_dwordx4 v166, v[70:73], s[18:19] offset:1024 sc0 sc1
	global_store_dwordx4 v166, v[74:77], s[18:19] offset:2048 sc0 sc1
	global_store_dwordx4 v166, v[78:81], s[18:19] offset:3072 sc0 sc1
	global_store_dwordx4 v167, v[82:85], s[18:19] offset:0 sc0 sc1
	global_store_dwordx4 v167, v[86:89], s[18:19] offset:1024 sc0 sc1
	global_store_dwordx4 v167, v[90:93], s[18:19] offset:2048 sc0 sc1
	global_store_dwordx4 v167, v[94:97], s[18:19] offset:3072 sc0 sc1
	global_store_dwordx4 v168, v[98:101], s[18:19] offset:0 sc0 sc1
	global_store_dwordx4 v168, v[102:105], s[18:19] offset:1024 sc0 sc1
	global_store_dwordx4 v168, v[106:109], s[18:19] offset:2048 sc0 sc1
	global_store_dwordx4 v168, v[110:113], s[18:19] offset:3072 sc0 sc1
	global_store_dwordx4 v169, v[114:117], s[18:19] offset:0 sc0 sc1
	global_store_dwordx4 v169, v[118:121], s[18:19] offset:1024 sc0 sc1
	global_store_dwordx4 v169, v[122:125], s[18:19] offset:2048 sc0 sc1
	global_store_dwordx4 v169, v[126:129], s[18:19] offset:3072 sc0 sc1
	s_waitcnt vmcnt(0)
	v_mov_b32_e32 v132, s22
	global_store_dword v170, v132, s[20:21] sc0 sc1
	s_waitcnt vmcnt(0)
	s_branch .LBB0_1033
